# gate-up GEMM epilogue: the eight row sum-of-squares loads issued together instead of eight serialised load/wait round trips
# speedup vs baseline: 1.0020x; 1.0020x over previous
.LBB0_238:
	s_lshl_b32 s20, s56, 7
	v_add_u32_e32 v152, s20, v154
	v_ashrrev_i32_e32 v153, 31, v152
	v_lshl_add_u64 v[200:201], v[152:153], 2, s[36:37]
	global_load_dword v176, v[200:201], off
	v_add_u32_e32 v202, s20, v157
	v_ashrrev_i32_e32 v203, 31, v202
	v_lshl_add_u64 v[202:203], v[202:203], 2, s[36:37]
	global_load_dword v177, v[202:203], off
	v_add_u32_e32 v202, s20, v158
	v_ashrrev_i32_e32 v203, 31, v202
	v_lshl_add_u64 v[202:203], v[202:203], 2, s[36:37]
	global_load_dword v178, v[202:203], off
	v_add_u32_e32 v202, s20, v159
	v_ashrrev_i32_e32 v203, 31, v202
	v_lshl_add_u64 v[202:203], v[202:203], 2, s[36:37]
	global_load_dword v179, v[202:203], off
	v_add_u32_e32 v202, 0x80, v152
	v_ashrrev_i32_e32 v203, 31, v202
	v_lshl_add_u64 v[202:203], v[202:203], 2, s[36:37]
	global_load_dword v180, v[202:203], off
	v_add_u32_e32 v202, 0x90, v152
	v_ashrrev_i32_e32 v203, 31, v202
	v_lshl_add_u64 v[202:203], v[202:203], 2, s[36:37]
	global_load_dword v181, v[202:203], off
	v_add_u32_e32 v202, 0xa0, v152
	v_ashrrev_i32_e32 v203, 31, v202
	v_lshl_add_u64 v[202:203], v[202:203], 2, s[36:37]
	global_load_dword v182, v[202:203], off
	v_add_u32_e32 v202, 0xb0, v152
	v_ashrrev_i32_e32 v203, 31, v202
	v_lshl_add_u64 v[202:203], v[202:203], 2, s[36:37]
	global_load_dword v183, v[202:203], off
	v_lshl_add_u64 v[144:145], v[152:153], 2, s[36:37]
	v_add_u32_e32 v150, 0x80, v152
	v_ashrrev_i32_e32 v151, 31, v150
	v_add_u32_e32 v148, 0x90, v152
	v_ashrrev_i32_e32 v149, 31, v148
	v_add_u32_e32 v146, 0xa0, v152
	v_ashrrev_i32_e32 v147, 31, v146
	v_pk_mul_f32 v[120:121], v[120:121], v[128:129]
	v_pk_mul_f32 v[118:119], v[118:119], v[126:127]
	v_pk_mul_f32 v[122:123], v[122:123], v[130:131]
	v_pk_mul_f32 v[116:117], v[116:117], v[124:125]
	v_pk_mul_f32 v[104:105], v[104:105], v[112:113]
	v_pk_mul_f32 v[106:107], v[106:107], v[114:115]
	v_pk_mul_f32 v[88:89], v[88:89], v[96:97]
	v_pk_mul_f32 v[90:91], v[90:91], v[98:99]
	v_pk_mul_f32 v[72:73], v[72:73], v[80:81]
	v_pk_mul_f32 v[74:75], v[74:75], v[82:83]
	v_pk_mul_f32 v[54:55], v[54:55], v[62:63]
	v_pk_mul_f32 v[56:57], v[56:57], v[64:65]
	v_pk_mul_f32 v[38:39], v[38:39], v[46:47]
	v_pk_mul_f32 v[40:41], v[40:41], v[48:49]
	v_pk_mul_f32 v[22:23], v[22:23], v[30:31]
	v_pk_mul_f32 v[24:25], v[24:25], v[32:33]
	s_waitcnt vmcnt(0)
	v_fmamk_f32 v144, v176, 0x3a000000, v1
	v_rsq_f32_e32 v174, v144
	v_add_u32_e32 v144, s20, v157
	v_ashrrev_i32_e32 v145, 31, v144
	v_lshl_add_u64 v[144:145], v[144:145], 2, s[36:37]
	v_mul_f32_e32 v166, 0xbfb8aa3b, v174
	v_pk_mul_f32 v[168:169], v[128:129], v[166:167] op_sel_hi:[1,0]
	v_pk_mul_f32 v[170:171], v[130:131], v[166:167] op_sel_hi:[1,0]
	v_exp_f32_e32 v168, v168
	v_exp_f32_e32 v169, v169
	v_exp_f32_e32 v170, v170
	v_exp_f32_e32 v171, v171
	v_pk_mul_f32 v[172:173], v[124:125], v[166:167] op_sel_hi:[1,0]
	v_pk_mul_f32 v[166:167], v[126:127], v[166:167] op_sel_hi:[1,0]
	v_exp_f32_e32 v172, v172
	v_exp_f32_e32 v173, v173
	v_exp_f32_e32 v166, v166
	v_exp_f32_e32 v167, v167
	v_pk_add_f32 v[168:169], v[168:169], 1.0 op_sel_hi:[1,0]
	v_pk_add_f32 v[128:129], v[170:171], 1.0 op_sel_hi:[1,0]
	v_rcp_f32_e32 v126, v168
	v_rcp_f32_e32 v127, v169
	v_rcp_f32_e32 v128, v128
	v_rcp_f32_e32 v129, v129
	v_pk_add_f32 v[130:131], v[172:173], 1.0 op_sel_hi:[1,0]
	v_pk_add_f32 v[124:125], v[166:167], 1.0 op_sel_hi:[1,0]
	v_rcp_f32_e32 v130, v130
	v_rcp_f32_e32 v131, v131
	v_mul_f32_e32 v166, v174, v174
	v_pk_mul_f32 v[126:127], v[166:167], v[126:127] op_sel_hi:[0,1]
	v_rcp_f32_e32 v124, v124
	v_rcp_f32_e32 v125, v125
	v_pk_mul_f32 v[120:121], v[120:121], v[126:127]
	v_pk_mul_f32 v[126:127], v[166:167], v[128:129] op_sel_hi:[0,1]
	v_pk_mul_f32 v[122:123], v[122:123], v[126:127]
	v_cvt_pk_bf16_f32 v120, v120, v121
	v_cvt_pk_bf16_f32 v121, v122, v123
	v_pk_mul_f32 v[122:123], v[166:167], v[130:131] op_sel_hi:[0,1]
	v_pk_mul_f32 v[116:117], v[116:117], v[122:123]
	v_or_b32_e32 v128, 16, v152
	v_cvt_pk_bf16_f32 v122, v116, v117
	v_pk_mul_f32 v[116:117], v[166:167], v[124:125] op_sel_hi:[0,1]
	v_pk_mul_f32 v[116:117], v[118:119], v[116:117]
	v_fmamk_f32 v144, v177, 0x3a000000, v1
	v_rsq_f32_e32 v165, v144
	v_add_u32_e32 v144, s20, v158
	v_ashrrev_i32_e32 v145, 31, v144
	v_lshl_add_u64 v[144:145], v[144:145], 2, s[36:37]
	v_cvt_pk_bf16_f32 v123, v116, v117
	v_mov_b64_e32 v[116:117], s[34:35]
	v_mad_i64_i32 v[124:125], s[22:23], v152, s93, v[116:117]
	v_fmamk_f32 v144, v178, 0x3a000000, v1
	v_rsq_f32_e32 v164, v144
	v_add_u32_e32 v144, s20, v159
	v_ashrrev_i32_e32 v145, 31, v144
	v_lshl_add_u64 v[144:145], v[144:145], 2, s[36:37]
	v_fmamk_f32 v144, v179, 0x3a000000, v1
	v_rsq_f32_e32 v163, v144
	v_lshl_add_u64 v[144:145], v[150:151], 2, s[36:37]
	v_fmamk_f32 v144, v180, 0x3a000000, v1
	v_rsq_f32_e32 v153, v144
	v_lshl_add_u64 v[144:145], v[148:149], 2, s[36:37]
	v_fmamk_f32 v144, v181, 0x3a000000, v1
	v_rsq_f32_e32 v151, v144
	v_lshl_add_u64 v[144:145], v[146:147], 2, s[36:37]
	v_fmamk_f32 v144, v182, 0x3a000000, v1
	v_rsq_f32_e32 v149, v144
	v_add_u32_e32 v144, 0xb0, v152
	v_ashrrev_i32_e32 v145, 31, v144
	v_lshl_add_u64 v[144:145], v[144:145], 2, s[36:37]
	v_fmamk_f32 v144, v183, 0x3a000000, v1
	v_rsq_f32_e32 v147, v144
	v_lshl_or_b32 v144, s54, 7, v162
	v_ashrrev_i32_e32 v145, 31, v144
	v_lshlrev_b64 v[118:119], 1, v[144:145]
	v_lshl_add_u64 v[124:125], v[124:125], 0, v[118:119]
	global_store_dwordx4 v[124:125], v[120:123], off
	s_nop 1
	v_mul_f32_e32 v120, 0xbfb8aa3b, v165
	v_pk_mul_f32 v[122:123], v[112:113], v[120:121] op_sel_hi:[1,0]
	v_pk_mul_f32 v[124:125], v[114:115], v[120:121] op_sel_hi:[1,0]
	v_exp_f32_e32 v122, v122
	v_exp_f32_e32 v123, v123
	v_exp_f32_e32 v124, v124
	v_exp_f32_e32 v125, v125
	v_pk_mul_f32 v[126:127], v[108:109], v[120:121] op_sel_hi:[1,0]
	v_pk_mul_f32 v[120:121], v[110:111], v[120:121] op_sel_hi:[1,0]
	v_exp_f32_e32 v126, v126
	v_exp_f32_e32 v127, v127
	v_exp_f32_e32 v120, v120
	v_exp_f32_e32 v121, v121
	v_pk_add_f32 v[122:123], v[122:123], 1.0 op_sel_hi:[1,0]
	v_pk_add_f32 v[112:113], v[124:125], 1.0 op_sel_hi:[1,0]
	v_pk_mul_f32 v[110:111], v[102:103], v[110:111]
	v_pk_mul_f32 v[102:103], v[100:101], v[108:109]
	v_rcp_f32_e32 v108, v122
	v_rcp_f32_e32 v109, v123
	v_rcp_f32_e32 v112, v112
	v_rcp_f32_e32 v113, v113
	v_pk_add_f32 v[114:115], v[126:127], 1.0 op_sel_hi:[1,0]
	v_pk_add_f32 v[100:101], v[120:121], 1.0 op_sel_hi:[1,0]
	v_rcp_f32_e32 v114, v114
	v_rcp_f32_e32 v115, v115
	v_mul_f32_e32 v122, v165, v165
	v_rcp_f32_e32 v120, v100
	v_rcp_f32_e32 v121, v101
	v_pk_mul_f32 v[100:101], v[122:123], v[108:109] op_sel_hi:[0,1]
	v_pk_mul_f32 v[100:101], v[104:105], v[100:101]
	v_pk_mul_f32 v[104:105], v[122:123], v[112:113] op_sel_hi:[0,1]
	v_pk_mul_f32 v[104:105], v[106:107], v[104:105]
	v_cvt_pk_bf16_f32 v100, v100, v101
	v_cvt_pk_bf16_f32 v101, v104, v105
	v_pk_mul_f32 v[104:105], v[122:123], v[114:115] op_sel_hi:[0,1]
	v_pk_mul_f32 v[102:103], v[102:103], v[104:105]
	v_pk_mul_f32 v[104:105], v[122:123], v[120:121] op_sel_hi:[0,1]
	v_pk_mul_f32 v[104:105], v[110:111], v[104:105]
	v_cvt_pk_bf16_f32 v102, v102, v103
	v_cvt_pk_bf16_f32 v103, v104, v105
	v_mad_i64_i32 v[104:105], s[22:23], v128, s93, v[116:117]
	v_lshl_add_u64 v[104:105], v[104:105], 0, v[118:119]
	global_store_dwordx4 v[104:105], v[100:103], off
	v_or_b32_e32 v108, 32, v152
	s_nop 0
	v_mul_f32_e32 v100, 0xbfb8aa3b, v164
	v_pk_mul_f32 v[102:103], v[96:97], v[100:101] op_sel_hi:[1,0]
	v_pk_mul_f32 v[104:105], v[98:99], v[100:101] op_sel_hi:[1,0]
	v_exp_f32_e32 v102, v102
	v_exp_f32_e32 v103, v103
	v_exp_f32_e32 v104, v104
	v_exp_f32_e32 v105, v105
	v_pk_mul_f32 v[106:107], v[92:93], v[100:101] op_sel_hi:[1,0]
	v_pk_mul_f32 v[100:101], v[94:95], v[100:101] op_sel_hi:[1,0]
	v_exp_f32_e32 v106, v106
	v_exp_f32_e32 v107, v107
	v_exp_f32_e32 v100, v100
	v_exp_f32_e32 v101, v101
	v_pk_add_f32 v[102:103], v[102:103], 1.0 op_sel_hi:[1,0]
	v_pk_add_f32 v[96:97], v[104:105], 1.0 op_sel_hi:[1,0]
	v_pk_mul_f32 v[94:95], v[86:87], v[94:95]
	v_pk_mul_f32 v[86:87], v[84:85], v[92:93]
	v_rcp_f32_e32 v92, v102
	v_rcp_f32_e32 v93, v103
	v_rcp_f32_e32 v96, v96
	v_rcp_f32_e32 v97, v97
	v_pk_add_f32 v[98:99], v[106:107], 1.0 op_sel_hi:[1,0]
	v_pk_add_f32 v[84:85], v[100:101], 1.0 op_sel_hi:[1,0]
	v_rcp_f32_e32 v98, v98
	v_rcp_f32_e32 v99, v99
	v_mul_f32_e32 v102, v164, v164
	v_rcp_f32_e32 v100, v84
	v_rcp_f32_e32 v101, v85
	v_pk_mul_f32 v[84:85], v[102:103], v[92:93] op_sel_hi:[0,1]
	v_pk_mul_f32 v[84:85], v[88:89], v[84:85]
	v_pk_mul_f32 v[88:89], v[102:103], v[96:97] op_sel_hi:[0,1]
	v_pk_mul_f32 v[88:89], v[90:91], v[88:89]
	v_cvt_pk_bf16_f32 v84, v84, v85
	v_cvt_pk_bf16_f32 v85, v88, v89
	v_pk_mul_f32 v[88:89], v[102:103], v[98:99] op_sel_hi:[0,1]
	v_pk_mul_f32 v[86:87], v[86:87], v[88:89]
	v_pk_mul_f32 v[88:89], v[102:103], v[100:101] op_sel_hi:[0,1]
	v_pk_mul_f32 v[88:89], v[94:95], v[88:89]
	v_cvt_pk_bf16_f32 v86, v86, v87
	v_cvt_pk_bf16_f32 v87, v88, v89
	v_mad_i64_i32 v[88:89], s[22:23], v108, s93, v[116:117]
	v_lshl_add_u64 v[88:89], v[88:89], 0, v[118:119]
	global_store_dwordx4 v[88:89], v[84:87], off
	v_or_b32_e32 v92, 48, v152
	s_nop 0
	v_mul_f32_e32 v84, 0xbfb8aa3b, v163
	v_pk_mul_f32 v[86:87], v[80:81], v[84:85] op_sel_hi:[1,0]
	v_pk_mul_f32 v[88:89], v[82:83], v[84:85] op_sel_hi:[1,0]
	v_exp_f32_e32 v86, v86
	v_exp_f32_e32 v87, v87
	v_exp_f32_e32 v88, v88
	v_exp_f32_e32 v89, v89
	v_pk_mul_f32 v[90:91], v[76:77], v[84:85] op_sel_hi:[1,0]
	v_pk_mul_f32 v[84:85], v[78:79], v[84:85] op_sel_hi:[1,0]
	v_exp_f32_e32 v90, v90
	v_exp_f32_e32 v91, v91
	v_exp_f32_e32 v84, v84
	v_exp_f32_e32 v85, v85
	v_pk_add_f32 v[86:87], v[86:87], 1.0 op_sel_hi:[1,0]
	v_pk_add_f32 v[80:81], v[88:89], 1.0 op_sel_hi:[1,0]
	v_pk_mul_f32 v[78:79], v[70:71], v[78:79]
	v_pk_mul_f32 v[70:71], v[68:69], v[76:77]
	v_rcp_f32_e32 v76, v86
	v_rcp_f32_e32 v77, v87
	v_rcp_f32_e32 v80, v80
	v_rcp_f32_e32 v81, v81
	v_pk_add_f32 v[82:83], v[90:91], 1.0 op_sel_hi:[1,0]
	v_pk_add_f32 v[68:69], v[84:85], 1.0 op_sel_hi:[1,0]
	v_rcp_f32_e32 v82, v82
	v_rcp_f32_e32 v83, v83
	v_mul_f32_e32 v86, v163, v163
	v_rcp_f32_e32 v84, v68
	v_rcp_f32_e32 v85, v69
	v_pk_mul_f32 v[68:69], v[86:87], v[76:77] op_sel_hi:[0,1]
	v_pk_mul_f32 v[68:69], v[72:73], v[68:69]
	v_pk_mul_f32 v[72:73], v[86:87], v[80:81] op_sel_hi:[0,1]
	v_pk_mul_f32 v[72:73], v[74:75], v[72:73]
	v_cvt_pk_bf16_f32 v68, v68, v69
	v_cvt_pk_bf16_f32 v69, v72, v73
	v_pk_mul_f32 v[72:73], v[86:87], v[82:83] op_sel_hi:[0,1]
	v_pk_mul_f32 v[70:71], v[70:71], v[72:73]
	v_pk_mul_f32 v[72:73], v[86:87], v[84:85] op_sel_hi:[0,1]
	v_pk_mul_f32 v[72:73], v[78:79], v[72:73]
	v_cvt_pk_bf16_f32 v70, v70, v71
	v_cvt_pk_bf16_f32 v71, v72, v73
	v_mad_i64_i32 v[72:73], s[22:23], v92, s93, v[116:117]
	v_lshl_add_u64 v[72:73], v[72:73], 0, v[118:119]
	global_store_dwordx4 v[72:73], v[68:71], off
	v_add_u32_e32 v85, s20, v160
	v_mul_f32_e32 v84, v147, v147
	v_mul_f32_e32 v68, 0xbfb8aa3b, v153
	v_pk_mul_f32 v[70:71], v[62:63], v[68:69] op_sel_hi:[1,0]
	v_pk_mul_f32 v[72:73], v[64:65], v[68:69] op_sel_hi:[1,0]
	v_exp_f32_e32 v70, v70
	v_exp_f32_e32 v71, v71
	v_exp_f32_e32 v72, v72
	v_exp_f32_e32 v73, v73
	v_pk_mul_f32 v[74:75], v[58:59], v[68:69] op_sel_hi:[1,0]
	v_pk_mul_f32 v[68:69], v[60:61], v[68:69] op_sel_hi:[1,0]
	v_exp_f32_e32 v74, v74
	v_exp_f32_e32 v75, v75
	v_exp_f32_e32 v68, v68
	v_exp_f32_e32 v69, v69
	v_pk_add_f32 v[70:71], v[70:71], 1.0 op_sel_hi:[1,0]
	v_pk_add_f32 v[62:63], v[72:73], 1.0 op_sel_hi:[1,0]
	v_pk_mul_f32 v[60:61], v[52:53], v[60:61]
	v_pk_mul_f32 v[52:53], v[50:51], v[58:59]
	v_rcp_f32_e32 v58, v70
	v_rcp_f32_e32 v59, v71
	v_rcp_f32_e32 v62, v62
	v_rcp_f32_e32 v63, v63
	v_pk_add_f32 v[64:65], v[74:75], 1.0 op_sel_hi:[1,0]
	v_pk_add_f32 v[50:51], v[68:69], 1.0 op_sel_hi:[1,0]
	v_rcp_f32_e32 v64, v64
	v_rcp_f32_e32 v65, v65
	v_mul_f32_e32 v70, v153, v153
	v_rcp_f32_e32 v68, v50
	v_rcp_f32_e32 v69, v51
	v_pk_mul_f32 v[50:51], v[70:71], v[58:59] op_sel_hi:[0,1]
	v_pk_mul_f32 v[50:51], v[54:55], v[50:51]
	v_pk_mul_f32 v[54:55], v[70:71], v[62:63] op_sel_hi:[0,1]
	v_pk_mul_f32 v[54:55], v[56:57], v[54:55]
	v_cvt_pk_bf16_f32 v50, v50, v51
	v_cvt_pk_bf16_f32 v51, v54, v55
	v_pk_mul_f32 v[54:55], v[70:71], v[64:65] op_sel_hi:[0,1]
	v_pk_mul_f32 v[52:53], v[52:53], v[54:55]
	v_pk_mul_f32 v[54:55], v[70:71], v[68:69] op_sel_hi:[0,1]
	v_pk_mul_f32 v[54:55], v[60:61], v[54:55]
	v_cvt_pk_bf16_f32 v52, v52, v53
	v_cvt_pk_bf16_f32 v53, v54, v55
	v_mad_i64_i32 v[54:55], s[22:23], v150, s93, v[116:117]
	v_lshl_add_u64 v[54:55], v[54:55], 0, v[118:119]
	global_store_dwordx4 v[54:55], v[50:53], off
	v_pk_mul_f32 v[70:71], v[8:9], v[16:17]
	v_pk_mul_f32 v[68:69], v[6:7], v[14:15]
	v_mul_f32_e32 v50, 0xbfb8aa3b, v151
	v_pk_mul_f32 v[52:53], v[46:47], v[50:51] op_sel_hi:[1,0]
	v_pk_mul_f32 v[54:55], v[48:49], v[50:51] op_sel_hi:[1,0]
	v_exp_f32_e32 v52, v52
	v_exp_f32_e32 v53, v53
	v_exp_f32_e32 v54, v54
	v_exp_f32_e32 v55, v55
	v_pk_mul_f32 v[56:57], v[42:43], v[50:51] op_sel_hi:[1,0]
	v_pk_mul_f32 v[50:51], v[44:45], v[50:51] op_sel_hi:[1,0]
	v_exp_f32_e32 v56, v56
	v_exp_f32_e32 v57, v57
	v_exp_f32_e32 v50, v50
	v_exp_f32_e32 v51, v51
	v_pk_add_f32 v[52:53], v[52:53], 1.0 op_sel_hi:[1,0]
	v_pk_add_f32 v[46:47], v[54:55], 1.0 op_sel_hi:[1,0]
	v_pk_mul_f32 v[44:45], v[36:37], v[44:45]
	v_pk_mul_f32 v[36:37], v[34:35], v[42:43]
	v_rcp_f32_e32 v42, v52
	v_rcp_f32_e32 v43, v53
	v_rcp_f32_e32 v46, v46
	v_rcp_f32_e32 v47, v47
	v_pk_add_f32 v[48:49], v[56:57], 1.0 op_sel_hi:[1,0]
	v_pk_add_f32 v[34:35], v[50:51], 1.0 op_sel_hi:[1,0]
	v_rcp_f32_e32 v48, v48
	v_rcp_f32_e32 v49, v49
	v_mul_f32_e32 v52, v151, v151
	v_rcp_f32_e32 v50, v34
	v_rcp_f32_e32 v51, v35
	v_pk_mul_f32 v[34:35], v[52:53], v[42:43] op_sel_hi:[0,1]
	v_pk_mul_f32 v[34:35], v[38:39], v[34:35]
	v_pk_mul_f32 v[38:39], v[52:53], v[46:47] op_sel_hi:[0,1]
	v_pk_mul_f32 v[38:39], v[40:41], v[38:39]
	v_cvt_pk_bf16_f32 v34, v34, v35
	v_cvt_pk_bf16_f32 v35, v38, v39
	v_pk_mul_f32 v[38:39], v[52:53], v[48:49] op_sel_hi:[0,1]
	v_pk_mul_f32 v[36:37], v[36:37], v[38:39]
	v_pk_mul_f32 v[38:39], v[52:53], v[50:51] op_sel_hi:[0,1]
	v_pk_mul_f32 v[38:39], v[44:45], v[38:39]
	v_cvt_pk_bf16_f32 v36, v36, v37
	v_cvt_pk_bf16_f32 v37, v38, v39
	v_mad_i64_i32 v[38:39], s[22:23], v148, s93, v[116:117]
	v_lshl_add_u64 v[38:39], v[38:39], 0, v[118:119]
	global_store_dwordx4 v[38:39], v[34:37], off
	v_pk_mul_f32 v[72:73], v[2:3], v[10:11]
	v_pk_mul_f32 v[74:75], v[4:5], v[12:13]
	v_mul_f32_e32 v34, 0xbfb8aa3b, v149
	v_pk_mul_f32 v[36:37], v[30:31], v[34:35] op_sel_hi:[1,0]
	v_pk_mul_f32 v[38:39], v[32:33], v[34:35] op_sel_hi:[1,0]
	v_exp_f32_e32 v36, v36
	v_exp_f32_e32 v37, v37
	v_exp_f32_e32 v38, v38
	v_exp_f32_e32 v39, v39
	v_pk_mul_f32 v[40:41], v[26:27], v[34:35] op_sel_hi:[1,0]
	v_pk_mul_f32 v[34:35], v[28:29], v[34:35] op_sel_hi:[1,0]
	v_exp_f32_e32 v40, v40
	v_exp_f32_e32 v41, v41
	v_exp_f32_e32 v34, v34
	v_exp_f32_e32 v35, v35
	v_pk_add_f32 v[36:37], v[36:37], 1.0 op_sel_hi:[1,0]
	v_pk_add_f32 v[30:31], v[38:39], 1.0 op_sel_hi:[1,0]
	v_pk_mul_f32 v[28:29], v[20:21], v[28:29]
	v_pk_mul_f32 v[20:21], v[18:19], v[26:27]
	v_rcp_f32_e32 v26, v36
	v_rcp_f32_e32 v27, v37
	v_rcp_f32_e32 v30, v30
	v_rcp_f32_e32 v31, v31
	v_pk_add_f32 v[32:33], v[40:41], 1.0 op_sel_hi:[1,0]
	v_pk_add_f32 v[18:19], v[34:35], 1.0 op_sel_hi:[1,0]
	v_rcp_f32_e32 v32, v32
	v_rcp_f32_e32 v33, v33
	v_mul_f32_e32 v36, v149, v149
	v_rcp_f32_e32 v34, v18
	v_rcp_f32_e32 v35, v19
	v_pk_mul_f32 v[18:19], v[36:37], v[26:27] op_sel_hi:[0,1]
	v_pk_mul_f32 v[18:19], v[22:23], v[18:19]
	v_pk_mul_f32 v[22:23], v[36:37], v[30:31] op_sel_hi:[0,1]
	v_pk_mul_f32 v[22:23], v[24:25], v[22:23]
	v_cvt_pk_bf16_f32 v18, v18, v19
	v_cvt_pk_bf16_f32 v19, v22, v23
	v_pk_mul_f32 v[22:23], v[36:37], v[32:33] op_sel_hi:[0,1]
	v_pk_mul_f32 v[20:21], v[20:21], v[22:23]
	v_pk_mul_f32 v[22:23], v[36:37], v[34:35] op_sel_hi:[0,1]
	v_pk_mul_f32 v[22:23], v[28:29], v[22:23]
	v_cvt_pk_bf16_f32 v20, v20, v21
	v_cvt_pk_bf16_f32 v21, v22, v23
	v_mad_i64_i32 v[22:23], s[22:23], v146, s93, v[116:117]
	v_lshl_add_u64 v[22:23], v[22:23], 0, v[118:119]
	global_store_dwordx4 v[22:23], v[18:21], off
	s_nop 1
	v_mul_f32_e32 v18, 0xbfb8aa3b, v147
	v_pk_mul_f32 v[20:21], v[14:15], v[18:19] op_sel_hi:[1,0]
	v_pk_mul_f32 v[22:23], v[16:17], v[18:19] op_sel_hi:[1,0]
	v_pk_mul_f32 v[24:25], v[10:11], v[18:19] op_sel_hi:[1,0]
	v_pk_mul_f32 v[18:19], v[12:13], v[18:19] op_sel_hi:[1,0]
	v_exp_f32_e32 v20, v20
	v_exp_f32_e32 v21, v21
	v_exp_f32_e32 v22, v22
	v_exp_f32_e32 v23, v23
	v_exp_f32_e32 v24, v24
	v_exp_f32_e32 v25, v25
	v_exp_f32_e32 v18, v18
	v_exp_f32_e32 v19, v19
	v_pk_add_f32 v[20:21], v[20:21], 1.0 op_sel_hi:[1,0]
	v_pk_add_f32 v[6:7], v[22:23], 1.0 op_sel_hi:[1,0]
	v_pk_add_f32 v[8:9], v[24:25], 1.0 op_sel_hi:[1,0]
	v_pk_add_f32 v[2:3], v[18:19], 1.0 op_sel_hi:[1,0]
	v_rcp_f32_e32 v82, v20
	v_rcp_f32_e32 v83, v21
	v_rcp_f32_e32 v80, v6
	v_rcp_f32_e32 v81, v7
	v_rcp_f32_e32 v78, v8
	v_rcp_f32_e32 v79, v9
	v_rcp_f32_e32 v76, v2
	v_rcp_f32_e32 v77, v3
	s_cbranch_execnz .LBB0_242
